# q up-projection GEMM moved into the rotary / mLSTM-chunk phase (half the workgroups before that phase's memory-bound work, half after); scan phase keeps the kv up-projection
# baseline (speedup 1.0000x reference)
; #define LAUNDER() int tid = tid0; asm volatile("" : "+v"(tid)); int wg = blockIdx.x; asm volatile("" : "+s"(wg)); const int lane = tid & 63, wave = __builtin_amdgcn_readfirstlane(tid >> 6), gw = wg * NWAVES + wave, NGW = G * NWAVES; (void)lane; (void)wave; (void)gw; (void)NGW
; __device__ __forceinline__ void phase_e1(bf16* Z, bf16* KR, int wg, int G, int wave, int lane, bool do_rope = true) {
;     const int n5 = (NB * 4 * NSTEP / 2) % G, tot5 = 4 * n5 + 5 * (G - n5);
;     const int c0 = wg < n5 ? 4 * wg : 4 * n5 + 5 * (wg - n5), c1 = wg + 1 < n5 ? 4 * (wg + 1) : 4 * n5 + 5 * (wg + 1 - n5);
;     const int rs = (int)(((long long)MTOK * c0) / tot5), re = (int)(((long long)MTOK * c1) / tot5);
; __global__ void __launch_bounds__(NTHR, 2) fwd_kernel(Args a) {
;     ...
;         { LAUNDER(); phase_e1(Z, KR, wg, G, wave, lane);
;           for (int i = wg * NTHR + tid; i < 5 * DFF; i += G * NTHR) { const int bp = i / DFF, cidx = i - bp * DFF; biasf[i] = (float)biasl[(size_t)bp * BIASW + DINP + cidx] * 2.3283064365386963e-10f; } }
;         { LAUNDER(); mlstm_a(Z, GATES, a.in[IN_GBIAS] + l * 16, DC, DN, SC, L, wg, G, tid); }
.LBB0_534:
	s_or_b64 exec, exec, s[2:3]
	s_mov_b32 s100, 9
	s_bitcmp1_b32 s48, 2
	s_cbranch_scc0 .Lp1_body
	s_mov_b32 s100, 5
	v_readlane_b32 s76, v252, 63
	v_readlane_b32 s77, v253, 0
	s_branch .LBB0_729
.Lp1_body:
	v_mov_b32_e32 v1, v0
	s_mov_b32 s18, s48
	v_readlane_b32 s2, v253, 54
	s_waitcnt lgkmcnt(0)
	s_barrier
	s_cmp_ge_i32 s18, s2
	v_readfirstlane_b32 s12, v1
	s_mov_b64 s[2:3], -1
	s_cbranch_scc0 .LBB0_536
	v_readlane_b32 s2, v253, 54
	s_sub_i32 s2, s18, s2
	s_mul_i32 s2, s2, 5
	v_readlane_b32 s3, v253, 55
	s_add_i32 s4, s2, s3
	s_mov_b64 s[2:3], 0

; #define GRID_BAR(id_) do { XcdBarrier b2_ = bar; unsigned xx_ = bar.x; asm volatile("" : "+s"(xx_)); b2_.x = xx_; xcd_barrier(b2_); } while (0)
; #define LAUNDER() int tid = tid0; asm volatile("" : "+v"(tid)); int wg = blockIdx.x; asm volatile("" : "+s"(wg)); const int lane = tid & 63, wave = __builtin_amdgcn_readfirstlane(tid >> 6), gw = wg * NWAVES + wave, NGW = G * NWAVES; (void)lane; (void)wave; (void)gw; (void)NGW
; __global__ void __launch_bounds__(NTHR, 2) fwd_kernel(Args a) {
;     ...
;         { LAUNDER(); phase_e1(Z, KR, wg, G, wave, lane);
;           for (int i = wg * NTHR + tid; i < 5 * DFF; i += G * NTHR) { const int bp = i / DFF, cidx = i - bp * DFF; biasf[i] = (float)biasl[(size_t)bp * BIASW + DINP + cidx] * 2.3283064365386963e-10f; } }
;         { LAUNDER(); mlstm_a(Z, GATES, a.in[IN_GBIAS] + l * 16, DC, DN, SC, L, wg, G, tid); }
;         GRID_BAR(3);
.LBB0_598:
	s_cmp_lg_u32 s100, 9
	s_cbranch_scc1 .Lbar3_go
	s_mov_b32 s100, 7
	s_branch .LBB0_729

;     __host__ __device__ void init(int N, int K, int G_, int c_, int mode_, int rev_ = 0) { so.init(128 * BM, N, K, G_, c_, rev_); nN = N / BM; mode = mode_; }
; #define GRID_BAR(id_) do { XcdBarrier b2_ = bar; unsigned xx_ = bar.x; asm volatile("" : "+s"(xx_)); b2_.x = xx_; xcd_barrier(b2_); } while (0)
; #define LAUNDER() int tid = tid0; asm volatile("" : "+v"(tid)); int wg = blockIdx.x; asm volatile("" : "+s"(wg)); const int lane = tid & 63, wave = __builtin_amdgcn_readfirstlane(tid >> 6), gw = wg * NWAVES + wave, NGW = G * NWAVES; (void)lane; (void)wave; (void)gw; (void)NGW
; __global__ void __launch_bounds__(NTHR, 2) fwd_kernel(Args a) {
;     ...
;         { LAUNDER(); phase_e1(Z, KR, wg, G, wave, lane);
;           for (int i = wg * NTHR + tid; i < 5 * DFF; i += G * NTHR) { const int bp = i / DFF, cidx = i - bp * DFF; biasf[i] = (float)biasl[(size_t)bp * BIASW + DINP + cidx] * 2.3283064365386963e-10f; } }
;         { LAUNDER(); mlstm_a(Z, GATES, a.in[IN_GBIAS] + l * 16, DC, DN, SC, L, wg, G, tid); }
;         GRID_BAR(3);
;         { LAUNDER(); mlstm_scan(DC, DN, SC, wg, G, tid); }
;         __syncthreads();
;         { LAUNDER(); pg8::Gemm g{Z + ZQ, WUQ, MTOK, 768, 512}; pg8::StaticOrder S; S.init(MTOK, 768, 512, G, wg, 1);
;           pg8::EpiBf16<0, false, true, 512, false> E{QM, 768, nullptr, rs2, nullptr, 0};
;           pg8::gemm_phase<pg8::EpiBf16<0, false, true, 512, false>, pg8::StaticOrder, true, true, DINP>(L, g, S, E); }
;         { LAUNDER(); pg8::Gemm g{Z + ZKV, WUKV, MTOK, 1024, 256}; pg8::StaticOrder S; S.init(MTOK, 1024, 256, G, (wg + 116) % G, 1);
.Luq_ret_b:
	s_mov_b32 s100, 6
	v_readlane_b32 s76, v252, 61
	v_readlane_b32 s77, v252, 62
	v_readlane_b32 s40, v254, 46
	v_readlane_b32 s30, v254, 63
	s_branch .Lp1_body
.Luq_ret_a:
	s_mov_b32 s100, 8
	s_branch .LBB0_598
.Lscan_exit:
	s_cmp_eq_u32 s100, 2
	s_cbranch_scc1 .Lbar4_go
	s_branch .LBB0_755

; #define PG8_WAIT_V(n) asm volatile("s_waitcnt vmcnt(" #n ")" ::: "memory")
; #define PG8_BAR __builtin_amdgcn_s_barrier()
;     ...
;     const int tid = tid_l, wid = __builtin_amdgcn_readfirstlane(tid >> 6), lane = tid & 63, wr = wid >> 2, wc = wid & 3, fr = lane & 15, fq = lane >> 4;
;     const int K = g.K; const int lda = LDA ? LDA : K;
;     unsigned voffA[2], voffB[2];
; #pragma unroll
;     for (int i = 0; i < 2; ++i) { int R, C; stage_rc(tid * 16 + i * 8192, R, C); const int Rb = Epi::PERM ? ((R & ~31) + perm32(R & 31)) : R;
;         voffA[i] = (unsigned)(R * lda + C) * 2u; voffB[i] = (unsigned)(Rb * K + C) * 2u; }
;     const size_t kstep = (size_t)(BK * 2);
;     const size_t hstep = (size_t)HALF * K * 2;
;     const size_t tstep = 2 * hstep;
;     const size_t hstepA = LDA ? (size_t)HALF * LDA * 2 : hstep, tstepA = 2 * hstepA;
;     const unsigned ldsw = (unsigned)wid * 1024u;
;     const int aoff = lds_byte(wr * 64 + fr, fq * 8), boff = lds_byte(wc * 32 + fr, fq * 8);
;     ...
;     Unit cur, nxt; int ui = 0;
;     if (!S.next(0, cur)) return;
;     f32x4 acc[2][2][4][2];
; #pragma unroll
;     for (int a = 0; a < 2; ++a)
; #pragma unroll
;         for (int b = 0; b < 2; ++b)
; #pragma unroll
;             for (int m = 0; m < 4; ++m)
; #pragma unroll
;                 for (int n = 0; n < 2; ++n) acc[a][b][m][n] = (f32x4){0.f, 0.f, 0.f, 0.f};
;     bf16x8 At[4][2], B0[2][2], B1[2][2];
;     int nt = cur.nt;
;     const char* cA = (const char*)g.A + (size_t)cur.pm * tstepA + (size_t)cur.k0 * kstep; const char* cB = (const char*)g.Bt + (size_t)cur.pn * tstep + (size_t)cur.k0 * kstep;
;     S.a_ready(cur);
;     if constexpr (SP2) {
;         PG8_STAGE(PG8_SB(0, 0), cB, voffB); PG8_STAGE(PG8_SB(0, 1), cB + hstep, voffB); PG8_STAGE(PG8_SA(0, 0), cA, voffA); PG8_STAGE(PG8_SA(0, 1), cA + hstepA, voffA);
;         if (wr == 1) PG8_BAR;
;         PG8_WAIT_V(2); PG8_BAR;
;         PG8_STAGE(PG8_SB(1, 0), cB + kstep, voffB); PG8_STAGE(PG8_SA(1, 0), cA + kstep, voffA); PG8_STAGE(PG8_SB(1, 1), cB + hstep + kstep, voffB);
;         PG8_WAIT_V(6); PG8_BAR;
;     } else {
;         PG8_STAGE(PG8_SB(0, 0), cB, voffB); PG8_STAGE(PG8_SA(0, 0), cA, voffA); PG8_STAGE(PG8_SB(0, 1), cB + hstep, voffB); PG8_STAGE(PG8_SA(0, 1), cA + hstepA, voffA);
;         if (wr == 1) PG8_BAR;
;         PG8_WAIT_V(4); PG8_BAR;
.LBB0_755:
	s_cmp_eq_u32 s100, 5
	s_cbranch_scc1 .Luq_ret_b
	s_cmp_eq_u32 s100, 7
	s_cbranch_scc1 .Luq_ret_a
	v_mov_b32_e32 v1, v0
	s_mov_b32 s2, s48
	s_addk_i32 s2, 0x74
	s_ashr_i32 s3, s2, 31
	s_abs_i32 s2, s2
	v_readlane_b32 s4, v253, 52
	s_mul_hi_u32 s4, s2, s4
	v_readlane_b32 s5, v253, 53
	s_mul_i32 s4, s4, s5
	s_sub_i32 s2, s2, s4
	s_sub_i32 s4, s2, s5
	s_cmp_ge_u32 s2, s5
	s_cselect_b32 s2, s4, s2
	s_sub_i32 s4, s2, s5
	s_cmp_ge_u32 s2, s5
	s_cselect_b32 s2, s4, s2
	s_xor_b32 s2, s2, s3
	s_sub_i32 s41, s2, s3
	v_mov_b32_e32 v10, v0
	s_cmpk_gt_i32 s41, 0x20f
	v_readfirstlane_b32 s2, v10
	s_mov_b32 s76, 0x48000
	s_mov_b32 s77, 0x58000
	s_cbranch_scc1 .LBB0_773
	v_lshlrev_b32_e32 v1, 4, v10
	v_add_u32_e32 v2, 0x2000, v1
	v_ashrrev_i32_e32 v3, 31, v2
	v_lshrrev_b32_e32 v3, 22, v3
	v_add_u32_e32 v3, v2, v3
	v_ashrrev_i32_e32 v3, 10, v3
	v_mul_i32_i24_e32 v4, 0x400, v3
	v_sub_u32_e32 v2, v2, v4
	v_lshrrev_b32_e32 v4, 4, v2
	v_bitop3_b32 v2, v4, v2, 32 bitop3:0x6c
	v_ashrrev_i32_e32 v4, 31, v2
	v_lshrrev_b32_e32 v4, 26, v4
	v_add_u32_e32 v4, v2, v4
	v_lshlrev_b32_e32 v6, 3, v3
	v_ashrrev_i32_e32 v5, 6, v4
	v_and_b32_e32 v6, -16, v6
	v_add_u32_e32 v6, v5, v6
	v_and_b32_e32 v5, 3, v5
	s_mov_b32 s5, 0x7fffe0
	v_lshrrev_b32_e32 v7, 2, v6
	v_lshlrev_b32_e32 v8, 1, v6
	v_and_or_b32 v5, v6, s5, v5
	v_and_b32_e32 v7, 4, v7
	v_and_b32_e32 v8, 24, v8
	v_and_b32_e32 v4, 0xc0, v4
	v_or3_b32 v5, v5, v7, v8
	v_lshlrev_b32_e32 v3, 5, v3
	v_sub_u32_e32 v2, v2, v4
	v_mov_b32_e32 v8, 1
	v_and_b32_e32 v3, 32, v3
	v_ashrrev_i16_sdwa v2, v8, sext(v2) dst_sel:DWORD dst_unused:UNUSED_PAD src0_sel:DWORD src1_sel:BYTE_0
	v_add_u32_sdwa v2, v3, sext(v2) dst_sel:DWORD dst_unused:UNUSED_PAD src0_sel:DWORD src1_sel:WORD_0
	v_lshlrev_b32_e32 v3, 1, v2
	s_movk_i32 s10, 0xf00
	v_lshl_add_u32 v30, v5, 9, v3
	v_mul_lo_u32 v3, v6, s10
	v_add_lshl_u32 v134, v2, v3, 1
	v_bfe_i32 v2, v10, 27, 1
	v_lshrrev_b32_e32 v2, 22, v2
	v_add_u32_e32 v2, v1, v2
	v_and_b32_e32 v2, 0xfffffc00, v2
	v_sub_u32_e32 v1, v1, v2
	v_lshrrev_b32_e32 v2, 4, v1
	v_ashrrev_i32_e32 v4, 31, v10
	v_bitop3_b32 v1, v2, v1, 32 bitop3:0x6c
	v_lshrrev_b32_e32 v4, 26, v4
	v_ashrrev_i32_e32 v2, 31, v1
	v_add_u32_e32 v4, v10, v4
	v_lshrrev_b32_e32 v2, 26, v2
	v_ashrrev_i32_e32 v4, 6, v4
	v_add_u32_e32 v2, v1, v2
	v_lshlrev_b32_e32 v5, 3, v4
	v_ashrrev_i32_e32 v3, 6, v2
	v_and_b32_e32 v5, -16, v5
	v_add_u32_e32 v5, v3, v5
	v_and_b32_e32 v3, 3, v3
	s_ashr_i32 s56, s41, 31
	v_and_or_b32 v3, v5, s5, v3
	s_lshr_b32 s5, s56, 29
	s_add_i32 s5, s41, s5
	s_and_b32 s6, s5, -8
	s_sub_i32 s6, s41, s6
	s_ashr_i32 s3, s2, 6
	s_ashr_i32 s5, s5, 3
	s_lshr_b32 s7, s6, 31
	s_ashr_i32 s4, s2, 8
	s_lshl_b32 s53, s3, 10
	s_sub_i32 s5, s7, s5
	s_cmp_lt_i32 s6, 0
	s_movk_i32 s7, 0x43
	s_cselect_b32 s7, s7, 0x42
	s_mul_i32 s6, s6, s7
	s_add_i32 s5, s5, s6
	s_addk_i32 s5, 0x41
	s_ashr_i32 s6, s5, 31
	s_lshr_b32 s6, s6, 28
	s_add_i32 s6, s5, s6
	s_ashr_i32 s7, s6, 4
	s_lshl_b32 s7, s7, 2
	v_and_b32_e32 v2, 0xc0, v2
	s_sub_i32 s8, 0x84, s7
	v_lshlrev_b32_e32 v4, 5, v4
	v_sub_u32_e32 v1, v1, v2
	s_min_i32 s8, s8, 4
	v_and_b32_e32 v4, 32, v4
	v_ashrrev_i16_sdwa v1, v8, sext(v1) dst_sel:DWORD dst_unused:UNUSED_PAD src0_sel:DWORD src1_sel:BYTE_0
	s_abs_i32 s9, s8
	v_lshrrev_b32_e32 v6, 2, v5
	v_lshlrev_b32_e32 v7, 1, v5
	v_add_u32_sdwa v1, v4, sext(v1) dst_sel:DWORD dst_unused:UNUSED_PAD src0_sel:DWORD src1_sel:WORD_0
	v_cvt_f32_u32_e32 v4, s9
	v_and_b32_e32 v6, 4, v6
	v_and_b32_e32 v7, 24, v7
	v_or3_b32 v3, v3, v6, v7
	v_lshlrev_b32_e32 v2, 1, v1
	v_lshl_add_u32 v32, v3, 9, v2
	v_mul_lo_u32 v2, v5, s10
	v_add_lshl_u32 v136, v1, v2, 1
	v_rcp_iflag_f32_e32 v1, v4
	s_sub_i32 s11, 0, s9
	s_and_b32 s6, s6, -16
	s_sub_i32 s5, s5, s6
	v_mul_f32_e32 v1, 0x4f7ffffe, v1
	v_cvt_u32_f32_e32 v1, v1
	s_abs_i32 s10, s5
	s_xor_b32 s6, s5, s8
	s_ashr_i32 s6, s6, 31
	v_readfirstlane_b32 s12, v1
	s_mul_i32 s11, s11, s12
	s_mul_hi_u32 s11, s12, s11
	s_add_i32 s12, s12, s11
	s_mul_hi_u32 s11, s10, s12
	s_mul_i32 s12, s11, s9
	s_sub_i32 s10, s10, s12
	s_add_i32 s12, s11, 1
	s_sub_i32 s13, s10, s9
	s_cmp_ge_u32 s10, s9
	s_cselect_b32 s11, s12, s11
	s_cselect_b32 s10, s13, s10
	s_add_i32 s12, s11, 1
	s_cmp_ge_u32 s10, s9
	s_cselect_b32 s9, s12, s11
	s_xor_b32 s9, s9, s6
	s_sub_i32 s18, s9, s6
	s_mul_i32 s6, s18, s8
	s_sub_i32 s5, s5, s6
	s_ashr_i32 s19, s18, 31
	s_add_i32 s50, s7, s5
	s_lshl_b64 s[6:7], s[18:19], 17
	v_readlane_b32 s10, v255, 5
	v_readlane_b32 s11, v255, 6
	s_add_u32 s22, s10, s6
	s_addc_u32 s23, s11, s7
	s_add_i32 s19, s53, 0
	s_add_i32 m0, s19, 0x10000
	s_mul_i32 s8, s50, 0x1e0000
	global_load_lds_dwordx4 v32, s[22:23]
	s_add_i32 m0, s19, 0x12000
	s_add_u32 s6, s22, 0x10000
	global_load_lds_dwordx4 v30, s[22:23]
	s_addc_u32 s7, s23, 0
	s_add_i32 m0, s19, 0x14000
	s_mul_hi_i32 s5, s50, 0x1e0000
	global_load_lds_dwordx4 v32, s[6:7]
	s_add_i32 m0, s19, 0x16000
	s_add_u32 s24, s72, s8
	s_addc_u32 s25, s73, s5
	s_add_i32 s74, s19, 0x2000
	global_load_lds_dwordx4 v30, s[6:7]
	s_mov_b32 m0, s19
	s_add_u32 s6, s24, 0xf0000
	global_load_lds_dwordx4 v136, s[24:25]
	s_mov_b32 m0, s74
	s_addc_u32 s7, s25, 0
	s_add_i32 s78, s19, 0x4000
	global_load_lds_dwordx4 v134, s[24:25]
	s_mov_b32 m0, s78
	s_add_i32 s79, s19, 0x6000
	global_load_lds_dwordx4 v136, s[6:7]
	s_mov_b32 m0, s79
	s_cmp_eq_u32 s4, 1
	global_load_lds_dwordx4 v134, s[6:7]
	s_cselect_b64 s[6:7], -1, 0
	v_mov_b32_e32 v31, v33
	v_mov_b32_e32 v137, v33
	v_mov_b32_e32 v135, v33
	v_writelane_b32 v254, s6, 53
	s_mov_b32 s82, 0x50000
	s_mov_b32 s0, 0x40000
	v_lshl_add_u64 v[6:7], s[22:23], 0, v[32:33]
	v_lshl_add_u64 v[4:5], s[22:23], 0, v[30:31]
	v_lshl_add_u64 v[2:3], s[24:25], 0, v[136:137]
	v_writelane_b32 v254, s7, 54
	s_cmp_lg_u32 s4, 1
	v_lshl_add_u64 v[8:9], s[24:25], 0, v[134:135]
	s_cbranch_scc1 .LBB0_758
	s_barrier
